# T41b: fused epilogue half-1 residual loads issued before the LDS-staging barrier (redundant vmcnt(0) dropped), T41 half-2 prefetch kept
# speedup vs baseline: 1.0153x; 1.0079x over previous
; #define LAS __attribute__((address_space(3)))
; DI unsigned pk2(float lo, float hi) { f32x2 v = {lo, hi}; return __builtin_bit_cast(unsigned, __builtin_convertvector(v, bf2_t)); }
; DI int fresh_lane() { int l; asm volatile("v_mbcnt_lo_u32_b32 %0, -1, 0\n\tv_mbcnt_hi_u32_b32 %0, -1, %0" : "=v"(l)); return l; }
;     DI void fused(const f32x4 (&acc)[2][2][4][2], const pg8::Unit& u, int wr, int wc, LAS unsigned char* lds) const {
;         const int lane_ = fresh_lane(), fr = lane_ & 15, fq = lane_ >> 4;
;         const int w8 = wr * 4 + wc;
; #pragma unroll
;         for (int ai = 0; ai < 2; ++ai) {
; #pragma unroll
;             for (int m = 0; m < 4; ++m)
; #pragma unroll
;                 for (int bj = 0; bj < 2; ++bj)
; #pragma unroll
;                     for (int n = 0; n < 2; ++n)
;                         *(LAS f32x4*)(lds + (size_t)(wr * 64 + m * 16 + fr) * 1040 + (bj * 128 + wc * 32 + n * 16 + 4 * fq) * 4) = acc[ai][bj][m][n];
;             __syncthreads();
;             const size_t g0 = (size_t)(u.pm * 256 + ai * 128 + w8 * 16) * DM + u.pn * 256 + lane_ * 4;
;             f32x4 xo[16];
; #pragma unroll
;             for (int rr = 0; rr < 16; ++rr) xo[rr] = *(const f32x4*)(xin + g0 + (size_t)rr * DM);
; #pragma unroll
;             for (int rr = 0; rr < 16; ++rr) {
;                 const f32x4 a = *(const LAS f32x4*)(lds + (size_t)(w8 * 16 + rr) * 1040 + lane_ * 16);
;                 const f32x4 v = a + xo[rr];
;                 *(f32x4*)(xout + g0 + (size_t)rr * DM) = v;
;                 if (XB) {
;                     *(u32x2*)(XB + g0 + (size_t)rr * DM) = (u32x2){pk2(v[0], v[1]), pk2(v[2], v[3])};
;                     float part = (v[0] * v[0] + v[1] * v[1]) + (v[2] * v[2] + v[3] * v[3]);
;                     part = wave_sum(part, lane_);
;                     if (lane_ < 4) ssq_next[(size_t)(u.pm * 256 + ai * 128 + w8 * 16 + rr) * 16 + u.pn * 4 + lane_] = (lane_ == 0) ? part : 0.f;
;                 }
;             }
.LBB0_585:
	s_lshl_b32 s0, s62, 7
	s_waitcnt vmcnt(0)
	s_barrier
	v_mbcnt_lo_u32_b32 v130, -1, 0
	v_mbcnt_hi_u32_b32 v130, -1, v130
	s_add_i32 s0, s0, 0
	v_and_b32_e32 v131, -16, v130
	s_lshl_b32 s1, s62, 4
	v_add_u32_e32 v131, s0, v131
	s_lshl_b32 s0, s74, 8
	s_or_b32 s2, s1, s59
	s_add_i32 s18, s0, s2
	s_lshl_b32 s0, s73, 8
	v_lshlrev_b32_e32 v132, 2, v130
	s_ashr_i32 s1, s0, 31
	v_ashrrev_i32_e32 v133, 31, v132
	v_and_or_b32 v0, v130, 15, s59
	v_lshl_add_u64 v[132:133], v[132:133], 0, s[0:1]
	s_movk_i32 s0, 0x410
	s_ashr_i32 s19, s18, 31
	v_mul_lo_u32 v0, v0, s0
	s_lshl_b64 s[0:1], s[18:19], 10
	v_lshl_add_u64 v[140:141], v[132:133], 0, s[0:1]
	v_add_u32_e32 v138, v131, v0
	v_lshlrev_b64 v[142:143], 2, v[140:141]
	ds_write_b128 v138, v[126:129]
	ds_write_b128 v138, v[122:125] offset:64
	ds_write_b128 v138, v[118:121] offset:512
	ds_write_b128 v138, v[114:117] offset:576
	ds_write_b128 v138, v[110:113] offset:16640
	ds_write_b128 v138, v[106:109] offset:16704
	ds_write_b128 v138, v[102:105] offset:17152
	ds_write_b128 v138, v[98:101] offset:17216
	ds_write_b128 v138, v[94:97] offset:33280
	ds_write_b128 v138, v[90:93] offset:33344
	ds_write_b128 v138, v[86:89] offset:33792
	ds_write_b128 v138, v[82:85] offset:33856
	ds_write_b128 v138, v[78:81] offset:49920
	ds_write_b128 v138, v[74:77] offset:49984
	ds_write_b128 v138, v[70:73] offset:50432
	ds_write_b128 v138, v[66:69] offset:50496
	v_lshl_add_u64 v[66:67], s[14:15], 0, v[142:143]
	v_mov_b32_e32 v226, 0x80000
	v_mov_b32_e32 v227, 0
	v_lshl_add_u64 v[224:225], v[66:67], 0, v[226:227]
	v_mov_b32_e32 v226, 0x2000
	s_movk_i32 s80, 0x2000
	v_add_co_u32_e32 v68, vcc, s80, v66
	s_movk_i32 s81, 0x4000
	s_nop 0
	v_addc_co_u32_e32 v69, vcc, 0, v67, vcc
	global_load_dwordx4 v[126:129], v[66:67], off nt
	global_load_dwordx4 v[122:125], v[68:69], off offset:-4096 nt
	global_load_dwordx4 v[118:121], v[68:69], off nt
	v_add_co_u32_e32 v68, vcc, s81, v66
	s_movk_i32 s0, 0x6000
	s_nop 0
	v_addc_co_u32_e32 v69, vcc, 0, v67, vcc
	global_load_dwordx4 v[114:117], v[68:69], off offset:-4096 nt
	global_load_dwordx4 v[110:113], v[68:69], off nt
	v_add_co_u32_e32 v68, vcc, s0, v66
	s_mov_b32 s0, 0x8000
	s_nop 0
	v_addc_co_u32_e32 v69, vcc, 0, v67, vcc
	global_load_dwordx4 v[106:109], v[68:69], off offset:-4096 nt
	global_load_dwordx4 v[102:105], v[68:69], off nt
	v_add_co_u32_e32 v68, vcc, s0, v66
	s_mov_b32 s0, 0xa000
	s_nop 0
	v_addc_co_u32_e32 v69, vcc, 0, v67, vcc
	global_load_dwordx4 v[98:101], v[68:69], off offset:-4096 nt
	global_load_dwordx4 v[94:97], v[68:69], off nt
	v_add_co_u32_e32 v68, vcc, s0, v66
	s_mov_b32 s0, 0xc000
	s_nop 0
	v_addc_co_u32_e32 v69, vcc, 0, v67, vcc
	global_load_dwordx4 v[90:93], v[68:69], off offset:-4096 nt
	global_load_dwordx4 v[86:89], v[68:69], off nt
	v_add_co_u32_e32 v68, vcc, s0, v66
	s_mov_b32 s0, 0xe000
	s_nop 0
	v_addc_co_u32_e32 v69, vcc, 0, v67, vcc
	global_load_dwordx4 v[82:85], v[68:69], off offset:-4096 nt
	global_load_dwordx4 v[78:81], v[68:69], off nt
	v_add_co_u32_e32 v68, vcc, s0, v66
	s_mov_b32 s0, 0xf000
	s_nop 0
	v_addc_co_u32_e32 v69, vcc, 0, v67, vcc
	v_add_co_u32_e32 v66, vcc, s0, v66
	global_load_dwordx4 v[74:77], v[68:69], off offset:-4096 nt
	global_load_dwordx4 v[70:73], v[68:69], off nt
	v_addc_co_u32_e32 v67, vcc, 0, v67, vcc
	global_load_dwordx4 v[66:69], v[66:67], off nt
	global_load_dwordx4 v[160:163], v[224:225], off nt
	v_lshl_add_u64 v[224:225], v[224:225], 0, v[226:227]
	global_load_dwordx4 v[164:167], v[224:225], off offset:-4096 nt
	global_load_dwordx4 v[168:171], v[224:225], off nt
	v_lshl_add_u64 v[224:225], v[224:225], 0, v[226:227]
	global_load_dwordx4 v[172:175], v[224:225], off offset:-4096 nt
	global_load_dwordx4 v[176:179], v[224:225], off nt
	v_lshl_add_u64 v[224:225], v[224:225], 0, v[226:227]
	global_load_dwordx4 v[180:183], v[224:225], off offset:-4096 nt
	global_load_dwordx4 v[184:187], v[224:225], off nt
	v_lshl_add_u64 v[224:225], v[224:225], 0, v[226:227]
	global_load_dwordx4 v[188:191], v[224:225], off offset:-4096 nt
	global_load_dwordx4 v[192:195], v[224:225], off nt
	v_lshl_add_u64 v[224:225], v[224:225], 0, v[226:227]
	global_load_dwordx4 v[196:199], v[224:225], off offset:-4096 nt
	global_load_dwordx4 v[200:203], v[224:225], off nt
	v_lshl_add_u64 v[224:225], v[224:225], 0, v[226:227]
	global_load_dwordx4 v[204:207], v[224:225], off offset:-4096 nt
	global_load_dwordx4 v[208:211], v[224:225], off nt
	v_lshl_add_u64 v[224:225], v[224:225], 0, v[226:227]
	global_load_dwordx4 v[212:215], v[224:225], off offset:-4096 nt
	global_load_dwordx4 v[216:219], v[224:225], off nt
	v_mov_b32_e32 v226, 0x1000
	v_lshl_add_u64 v[224:225], v[224:225], 0, v[226:227]
	global_load_dwordx4 v[220:223], v[224:225], off nt
	s_waitcnt lgkmcnt(0)
	s_barrier
	v_lshl_add_u32 v0, v130, 4, 0
	s_mulk_i32 s2, 0x410
	v_add_u32_e32 v0, s2, v0
	ds_read_b128 v[134:137], v0
	s_lshl_b32 s16, s73, 2
	s_mov_b32 s86, s60
	v_readlane_b32 s60, v255, 52
	v_cmp_gt_i32_e64 s[4:5], 4, v130
	v_cmp_eq_u32_e64 s[0:1], 0, v130
	s_ashr_i32 s17, s16, 31
	v_ashrrev_i32_e32 v131, 31, v130
	s_andn2_b64 vcc, exec, s[8:9]
	s_mov_b32 s97, s94
	v_readlane_b32 s37, v255, 51
	v_readlane_b32 s61, v255, 53
	s_waitcnt vmcnt(31) lgkmcnt(0)
	v_pk_add_f32 v[126:127], v[126:127], v[134:135]
	v_cndmask_b32_e64 v134, 0, 1, s[8:9]
	v_pk_add_f32 v[128:129], v[128:129], v[136:137]
	v_lshl_add_u64 v[136:137], s[48:49], 0, v[142:143]
	v_cmp_ne_u32_e64 s[6:7], 1, v134
	v_lshl_add_u64 v[134:135], v[140:141], 1, s[12:13]
	global_store_dwordx4 v[136:137], v[126:129], off nt
	s_cbranch_vccnz .LBB0_589
	v_cvt_pk_bf16_f32 v140, v126, v127
	v_mul_f32_e32 v127, v127, v127
	v_fmac_f32_e32 v127, v126, v126
	v_mul_f32_e32 v126, v129, v129
	v_fmac_f32_e32 v126, v128, v128
	v_add_f32_e32 v126, v127, v126
	v_cvt_pk_bf16_f32 v141, v128, v129
	flat_store_dwordx2 v[134:135], v[140:141]
	v_add_f32_dpp v126, v126, v126 row_ror:1 row_mask:0xf bank_mask:0xf bound_ctrl:1
	s_nop 1
	v_add_f32_dpp v126, v126, v126 row_ror:2 row_mask:0xf bank_mask:0xf bound_ctrl:1
	s_nop 1
	v_add_f32_dpp v126, v126, v126 row_ror:4 row_mask:0xf bank_mask:0xf bound_ctrl:1
	s_nop 1
	v_add_f32_dpp v126, v126, v126 row_ror:8 row_mask:0xf bank_mask:0xf bound_ctrl:1
	s_nop 0
	v_readlane_b32 s24, v126, 0
	v_readlane_b32 s2, v126, 16
	v_readlane_b32 s25, v126, 32
	v_readlane_b32 s3, v126, 48
	s_and_saveexec_b64 s[22:23], s[4:5]
	s_cbranch_execz .LBB0_588
	v_mov_b32_e32 v126, s2
	v_mov_b32_e32 v127, s3
	s_lshl_b64 s[2:3], s[18:19], 6
	s_add_u32 s19, s10, s2
	s_addc_u32 s20, s11, s3
	s_lshl_b64 s[2:3], s[16:17], 2
	v_pk_add_f32 v[126:127], s[24:25], v[126:127]
	s_add_u32 s2, s19, s2
	v_add_f32_e32 v126, v126, v127
	s_addc_u32 s3, s20, s3
	v_cndmask_b32_e64 v128, 0, v126, s[0:1]
	v_lshl_add_u64 v[126:127], v[130:131], 2, s[2:3]
	flat_store_dword v[126:127], v128
